# lean10 = lean9 + pooling loop: per-level weight loads issued at the start of the second half of the iteration instead of right before their use
# speedup vs baseline: 1.0059x; 1.0059x over previous
; #define LAS __attribute__((address_space(3)))
; __device__ __forceinline__ void pool_compute(const PoolIn& I, u16* YA, const float* pscale, LAS unsigned char* lds, int un, int tid) {
;     ...
;     { const int w = 2 << g, t = rr, tpos = tb * 64 + t; const float rc = 1.0f / (float)(tpos + 1 < w ? tpos + 1 : w);
;         float s[8], u0[8];
; #pragma unroll
;         for (int i = 0; i < 8; ++i) { u0[i] = Uf[(16 + t) * 65 + cg8 + i]; s[i] = u0[i] + Uf[(15 + t) * 65 + cg8 + i]; }
;         if (g >= 1) {
; #pragma unroll
;             for (int i = 0; i < 8; ++i) s[i] += Uf[(14 + t) * 65 + cg8 + i] + Uf[(13 + t) * 65 + cg8 + i]; }
;         if (g >= 2) {
; #pragma unroll
;             for (int i = 0; i < 8; ++i) s[i] += (Uf[(12 + t) * 65 + cg8 + i] + Uf[(11 + t) * 65 + cg8 + i]) + (Uf[(10 + t) * 65 + cg8 + i] + Uf[(9 + t) * 65 + cg8 + i]); }
;         if (g >= 3) {
; #pragma unroll
;             for (int i = 0; i < 8; ++i) { float a = 0.f;
; #pragma unroll
;                 for (int j = 8; j < 16; ++j) a += Uf[(16 + t - j) * 65 + cg8 + i];
;                 s[i] += a; } }
;         float p[8];
; #pragma unroll
;         for (int i = 0; i < 8; ++i) p[i] = s[i] * rc - u0[i];
;         *(LAS v4u*)(Pb + t * PLP + cg8) = pack8(p); }
;     LBAR();
;     {
;         const int tr = wave >> 1, tc0 = (wave & 1) * 2, fr = lane & 15, fq = lane >> 4;
;         v4f a0 = {0.f, 0.f, 0.f, 0.f}, a1 = {0.f, 0.f, 0.f, 0.f};
; #pragma unroll
;         for (int kk = 0; kk < 2; ++kk) { const v8s a = *(const LAS v8s*)(Pb + (16 * tr + fr) * PLP + 32 * kk + 8 * fq);
;             a0 = __builtin_amdgcn_mfma_f32_16x16x32_bf16(a, *(const LAS v8s*)(WgT + (16 * tc0 + fr) * PLP + 32 * kk + 8 * fq), a0, 0, 0, 0);
;             a1 = __builtin_amdgcn_mfma_f32_16x16x32_bf16(a, *(const LAS v8s*)(WgT + (16 * tc0 + 16 + fr) * PLP + 32 * kk + 8 * fq), a1, 0, 0, 0); }
; #pragma unroll
;         for (int rg = 0; rg < 4; ++rg) { const int t = 16 * tr + 4 * fq + rg; Uf[t * 65 + 16 * tc0 + fr] = a0[rg]; Uf[t * 65 + 16 * tc0 + 16 + fr] = a1[rg]; } }
;     LBAR();
;     { const int t = rr; float o[8];
; #pragma unroll
;         for (int i = 0; i < 8; ++i) o[i] = Uf[t * 65 + cg8 + i] * pscale[g * 64 + cg8 + i];
;         *(v4u*)(YA + tl(r0 + t, g * 64 + cg8, 256)) = pack8(o); }
.LBB0_1106:
	v_lshl_or_b32 v110, s8, 6, v40
	v_ashrrev_i32_e32 v111, 31, v110
	v_lshl_add_u64 v[110:111], v[110:111], 2, s[4:5]
	global_load_dwordx4 v[112:115], v[110:111], off offset:16
	global_load_dwordx4 v[116:119], v[110:111], off
	v_add_u32_e32 v45, 1, v45
	s_lshl_b32 s9, 2, s8
	v_min_i32_e32 v45, s9, v45
	v_cvt_f32_i32_e32 v45, v45
	s_and_b32 s9, s10, 0x3fc0
	s_mov_b32 s15, s14
	v_div_scale_f32 v46, s[16:17], v45, v45, 1.0
	v_rcp_f32_e32 v47, v46
	s_nop 0
	v_fma_f32 v48, -v46, v47, 1.0
	v_fmac_f32_e32 v47, v48, v47
	v_div_scale_f32 v48, vcc, 1.0, v45, 1.0
	v_mul_f32_e32 v49, v48, v47
	v_fma_f32 v50, -v46, v49, v48
	v_fmac_f32_e32 v49, v50, v47
	v_fma_f32 v46, -v46, v49, v48
	v_div_fmas_f32 v46, v46, v47, v49
	v_div_fixup_f32 v46, v46, v45, 1.0
	v_pk_fma_f32 v[18:19], v[46:47], v[30:31], v[18:19] op_sel_hi:[0,1,1] neg_lo:[0,0,1] neg_hi:[0,0,1]
	v_pk_fma_f32 v[28:29], v[46:47], v[28:29], v[16:17] op_sel_hi:[0,1,1] neg_lo:[0,0,1] neg_hi:[0,0,1]
	v_pk_fma_f32 v[22:23], v[46:47], v[26:27], v[22:23] op_sel_hi:[0,1,1] neg_lo:[0,0,1] neg_hi:[0,0,1]
	v_pk_fma_f32 v[20:21], v[46:47], v[24:25], v[20:21] op_sel_hi:[0,1,1] neg_lo:[0,0,1] neg_hi:[0,0,1]
	v_cvt_pk_bf16_f32 v16, v18, v19
	v_cvt_pk_bf16_f32 v17, v28, v29
	v_cvt_pk_bf16_f32 v18, v22, v23
	v_cvt_pk_bf16_f32 v19, v20, v21
	ds_write_b128 v44, v[16:19] offset:20800
	s_waitcnt lgkmcnt(0)
	s_barrier
	ds_read_b128 v[16:19], v38 offset:20800
	ds_read_b128 v[20:23], v39 offset:30016
	ds_read_b128 v[24:27], v39 offset:32320
	s_waitcnt lgkmcnt(1)
	v_mfma_f32_16x16x32_bf16 v[20:23], v[16:19], v[20:23], 0
	s_waitcnt lgkmcnt(0)
	v_mfma_f32_16x16x32_bf16 v[16:19], v[16:19], v[24:27], 0
	ds_read_b128 v[24:27], v38 offset:20864
	ds_read_b128 v[28:31], v39 offset:30080
	s_waitcnt lgkmcnt(0)
	v_mfma_f32_16x16x32_bf16 v[20:23], v[24:27], v[28:31], v[20:23]
	ds_read_b128 v[28:31], v39 offset:32384
	s_waitcnt lgkmcnt(0)
	v_mfma_f32_16x16x32_bf16 v[16:19], v[24:27], v[28:31], v[16:19]
	s_nop 7
	ds_write2_b32 v42, v20, v16 offset1:16
	ds_write2_b32 v42, v21, v17 offset0:65 offset1:81
	ds_write2_b32 v42, v22, v18 offset0:130 offset1:146
	ds_write2_b32 v42, v23, v19 offset0:195 offset1:211
	v_lshl_or_b32 v16, s8, 6, v40
	v_ashrrev_i32_e32 v17, 31, v16
	s_waitcnt lgkmcnt(0)
	s_barrier
	v_lshl_add_u64 v[20:21], v[16:17], 2, s[4:5]
	ds_read2_b32 v[24:25], v37 offset1:1
	s_waitcnt vmcnt(5)
	v_mov_b64_e32 v[30:31], v[2:3]
	v_mov_b64_e32 v[28:29], v[0:1]
	s_waitcnt vmcnt(0) lgkmcnt(0)
	v_pk_mul_f32 v[20:21], v[24:25], v[116:117]
	ds_read2_b32 v[24:25], v37 offset0:2 offset1:3
	s_waitcnt lgkmcnt(0)
	v_pk_mul_f32 v[22:23], v[24:25], v[118:119]
	ds_read2_b32 v[24:25], v37 offset0:4 offset1:5
	s_waitcnt lgkmcnt(0)
	v_pk_mul_f32 v[24:25], v[24:25], v[112:113]
	ds_read2_b32 v[16:17], v37 offset0:6 offset1:7
	s_waitcnt lgkmcnt(0)
	v_pk_mul_f32 v[26:27], v[16:17], v[114:115]
	v_cvt_pk_bf16_f32 v17, v22, v23
	v_add_u32_e32 v22, s9, v41
	s_ashr_i32 s9, s8, 31
	v_cvt_pk_bf16_f32 v16, v20, v21
	v_ashrrev_i32_e32 v20, 8, v22
	v_lshlrev_b32_e32 v22, 6, v22
	s_lshl_b64 s[8:9], s[8:9], 15
	v_and_or_b32 v22, v22, s86, v40
	s_add_u32 s8, s11, s8
	v_ashrrev_i32_e32 v21, 31, v20
	s_addc_u32 s9, s12, s9
	v_lshlrev_b32_e32 v220, 1, v22
	v_lshl_add_u64 v[22:23], s[8:9], 0, v[220:221]
	v_lshlrev_b64 v[20:21], 17, v[20:21]
	v_cvt_pk_bf16_f32 v18, v24, v25
	v_cvt_pk_bf16_f32 v19, v26, v27
	v_lshl_add_u64 v[20:21], v[22:23], 0, v[20:21]
	global_store_dwordx4 v[20:21], v[16:19], off
	s_waitcnt lgkmcnt(0)
	s_barrier
	v_mov_b64_e32 v[22:23], v[14:15]
	v_mov_b64_e32 v[18:19], v[10:11]
	v_mov_b64_e32 v[26:27], v[6:7]
	s_add_i32 s10, s10, s13
	s_and_b64 vcc, exec, s[6:7]
	v_mov_b64_e32 v[16:17], v[8:9]
	v_mov_b64_e32 v[20:21], v[12:13]
	v_mov_b64_e32 v[24:25], v[4:5]
	s_cbranch_vccnz .LBB0_1115
